# t8 + G1a/G1b unit boundary: waves 0-3 run the SwiGLU epilogue before the alignment barrier (overlaps waves 4-7 last MFMA segment)
# baseline (speedup 1.0000x reference)
TB_L8579_exit:
.LBB0_518:
	v_exp_f32_e32 v140, v122
	v_exp_f32_e32 v141, v123
	v_pk_mul_f32 v[122:123], v[126:127], v[122:123]
	v_exp_f32_e32 v126, v114
	v_exp_f32_e32 v127, v115
	v_pk_mul_f32 v[114:115], v[118:119], v[114:115]
	v_pk_mul_f32 v[128:129], v[128:129], v[124:125]
	v_add_f32_e32 v126, 1.0, v126
	v_add_f32_e32 v127, 1.0, v127
	v_rcp_f32_e32 v126, v126
	v_rcp_f32_e32 v127, v127
	v_exp_f32_e32 v124, v124
	v_exp_f32_e32 v125, v125
	s_lshl_b32 s11, s58, 8
	v_pk_mul_f32 v[118:119], v[114:115], v[126:127]
	v_exp_f32_e32 v114, v116
	v_exp_f32_e32 v115, v117
	v_mbcnt_lo_u32_b32 v130, -1, 0
	v_mbcnt_hi_u32_b32 v130, -1, v130
	s_add_i32 s11, s11, s36
	v_add_f32_e32 v140, 1.0, v140
	v_add_f32_e32 v141, 1.0, v141
	v_add_f32_e32 v124, 1.0, v124
	v_add_f32_e32 v125, 1.0, v125
	v_add_f32_e32 v114, 1.0, v114
	v_add_f32_e32 v115, 1.0, v115
	v_and_or_b32 v135, v130, 15, s11
	s_lshl_b32 s11, s56, 7
	v_lshrrev_b32_e32 v130, 1, v130
	v_rcp_f32_e32 v140, v140
	v_rcp_f32_e32 v141, v141
	v_rcp_f32_e32 v124, v124
	v_rcp_f32_e32 v125, v125
	v_rcp_f32_e32 v114, v114
	v_rcp_f32_e32 v115, v115
	v_and_or_b32 v130, v130, 24, s11
	v_readlane_b32 s18, v255, 26
	v_or_b32_e32 v136, s37, v130
	v_readlane_b32 s19, v255, 27
	v_ashrrev_i32_e32 v137, 31, v136
	v_pk_mul_f32 v[120:121], v[120:121], v[116:117]
	v_mov_b64_e32 v[130:131], s[18:19]
	v_mad_i64_i32 v[138:139], s[18:19], v135, s85, v[130:131]
	v_pk_mul_f32 v[122:123], v[122:123], v[140:141]
	v_pk_mul_f32 v[124:125], v[128:129], v[124:125]
	v_pk_mul_f32 v[120:121], v[120:121], v[114:115]
	v_lshlrev_b64 v[114:115], 1, v[136:137]
	v_lshl_add_u64 v[126:127], v[138:139], 0, v[114:115]
	v_cvt_pk_bf16_f32 v116, v122, v123
	v_cvt_pk_bf16_f32 v117, v124, v125
	v_cvt_pk_bf16_f32 v118, v118, v119
	v_cvt_pk_bf16_f32 v119, v120, v121
	global_store_dwordx4 v[126:127], v[116:119], off
	v_pk_mul_f32 v[112:113], v[112:113], v[108:109]
	v_exp_f32_e32 v108, v108
	v_exp_f32_e32 v118, v106
	v_exp_f32_e32 v119, v107
	v_pk_mul_f32 v[106:107], v[110:111], v[106:107]
	v_exp_f32_e32 v110, v98
	v_exp_f32_e32 v111, v99
	v_pk_mul_f32 v[98:99], v[102:103], v[98:99]
	v_exp_f32_e32 v109, v109
	v_add_f32_e32 v110, 1.0, v110
	v_add_f32_e32 v111, 1.0, v111
	v_rcp_f32_e32 v110, v110
	v_rcp_f32_e32 v111, v111
	v_add_f32_e32 v118, 1.0, v118
	v_add_f32_e32 v119, 1.0, v119
	v_add_f32_e32 v108, 1.0, v108
	v_pk_mul_f32 v[102:103], v[98:99], v[110:111]
	v_exp_f32_e32 v98, v100
	v_exp_f32_e32 v99, v101
	v_add_f32_e32 v109, 1.0, v109
	v_rcp_f32_e32 v118, v118
	v_add_f32_e32 v98, 1.0, v98
	v_add_f32_e32 v99, 1.0, v99
	v_rcp_f32_e32 v119, v119
	v_rcp_f32_e32 v108, v108
	v_rcp_f32_e32 v109, v109
	v_rcp_f32_e32 v98, v98
	v_rcp_f32_e32 v99, v99
	v_or_b32_e32 v116, 16, v135
	v_pk_mul_f32 v[104:105], v[104:105], v[100:101]
	v_mad_i64_i32 v[116:117], s[18:19], v116, s85, v[130:131]
	v_pk_mul_f32 v[106:107], v[106:107], v[118:119]
	v_pk_mul_f32 v[108:109], v[112:113], v[108:109]
	v_pk_mul_f32 v[104:105], v[104:105], v[98:99]
	v_lshl_add_u64 v[110:111], v[116:117], 0, v[114:115]
	v_cvt_pk_bf16_f32 v98, v106, v107
	v_cvt_pk_bf16_f32 v99, v108, v109
	v_cvt_pk_bf16_f32 v100, v102, v103
	v_cvt_pk_bf16_f32 v101, v104, v105
	global_store_dwordx4 v[110:111], v[98:101], off
	v_pk_mul_f32 v[96:97], v[96:97], v[92:93]
	v_exp_f32_e32 v92, v92
	v_exp_f32_e32 v100, v90
	v_exp_f32_e32 v101, v91
	v_pk_mul_f32 v[90:91], v[94:95], v[90:91]
	v_exp_f32_e32 v94, v82
	v_exp_f32_e32 v95, v83
	v_pk_mul_f32 v[82:83], v[86:87], v[82:83]
	v_exp_f32_e32 v93, v93
	v_add_f32_e32 v94, 1.0, v94
	v_add_f32_e32 v95, 1.0, v95
	v_rcp_f32_e32 v94, v94
	v_rcp_f32_e32 v95, v95
	v_add_f32_e32 v100, 1.0, v100
	v_add_f32_e32 v101, 1.0, v101
	v_add_f32_e32 v92, 1.0, v92
	v_pk_mul_f32 v[86:87], v[82:83], v[94:95]
	v_exp_f32_e32 v82, v84
	v_exp_f32_e32 v83, v85
	v_add_f32_e32 v93, 1.0, v93
	v_rcp_f32_e32 v100, v100
	v_add_f32_e32 v82, 1.0, v82
	v_add_f32_e32 v83, 1.0, v83
	v_rcp_f32_e32 v101, v101
	v_rcp_f32_e32 v92, v92
	v_rcp_f32_e32 v93, v93
	v_rcp_f32_e32 v82, v82
	v_rcp_f32_e32 v83, v83
	v_or_b32_e32 v98, 32, v135
	v_pk_mul_f32 v[88:89], v[88:89], v[84:85]
	v_mad_i64_i32 v[98:99], s[18:19], v98, s85, v[130:131]
	v_pk_mul_f32 v[90:91], v[90:91], v[100:101]
	v_pk_mul_f32 v[92:93], v[96:97], v[92:93]
	v_pk_mul_f32 v[88:89], v[88:89], v[82:83]
	v_lshl_add_u64 v[94:95], v[98:99], 0, v[114:115]
	v_cvt_pk_bf16_f32 v82, v90, v91
	v_cvt_pk_bf16_f32 v83, v92, v93
	v_cvt_pk_bf16_f32 v84, v86, v87
	v_cvt_pk_bf16_f32 v85, v88, v89
	global_store_dwordx4 v[94:95], v[82:85], off
	v_pk_mul_f32 v[80:81], v[80:81], v[76:77]
	v_exp_f32_e32 v76, v76
	v_exp_f32_e32 v84, v74
	v_exp_f32_e32 v85, v75
	v_pk_mul_f32 v[74:75], v[78:79], v[74:75]
	v_exp_f32_e32 v78, v66
	v_exp_f32_e32 v79, v67
	v_pk_mul_f32 v[66:67], v[70:71], v[66:67]
	v_exp_f32_e32 v77, v77
	v_add_f32_e32 v78, 1.0, v78
	v_add_f32_e32 v79, 1.0, v79
	v_rcp_f32_e32 v78, v78
	v_rcp_f32_e32 v79, v79
	v_add_f32_e32 v84, 1.0, v84
	v_add_f32_e32 v85, 1.0, v85
	v_add_f32_e32 v76, 1.0, v76
	v_pk_mul_f32 v[70:71], v[66:67], v[78:79]
	v_exp_f32_e32 v66, v68
	v_exp_f32_e32 v67, v69
	v_add_f32_e32 v77, 1.0, v77
	v_rcp_f32_e32 v84, v84
	v_add_f32_e32 v66, 1.0, v66
	v_add_f32_e32 v67, 1.0, v67
	v_rcp_f32_e32 v85, v85
	v_rcp_f32_e32 v76, v76
	v_rcp_f32_e32 v77, v77
	v_rcp_f32_e32 v66, v66
	v_rcp_f32_e32 v67, v67
	v_or_b32_e32 v82, 48, v135
	v_pk_mul_f32 v[72:73], v[72:73], v[68:69]
	v_mad_i64_i32 v[82:83], s[18:19], v82, s85, v[130:131]
	v_pk_mul_f32 v[74:75], v[74:75], v[84:85]
	v_pk_mul_f32 v[76:77], v[80:81], v[76:77]
	v_pk_mul_f32 v[72:73], v[72:73], v[66:67]
	v_lshl_add_u64 v[78:79], v[82:83], 0, v[114:115]
	v_cvt_pk_bf16_f32 v66, v74, v75
	v_cvt_pk_bf16_f32 v67, v76, v77
	v_cvt_pk_bf16_f32 v68, v70, v71
	v_cvt_pk_bf16_f32 v69, v72, v73
	global_store_dwordx4 v[78:79], v[66:69], off
	v_pk_mul_f32 v[64:65], v[64:65], v[60:61]
	v_exp_f32_e32 v60, v60
	v_exp_f32_e32 v68, v58
	v_exp_f32_e32 v69, v59
	v_pk_mul_f32 v[58:59], v[62:63], v[58:59]
	v_exp_f32_e32 v62, v50
	v_exp_f32_e32 v63, v51
	v_pk_mul_f32 v[50:51], v[54:55], v[50:51]
	v_exp_f32_e32 v61, v61
	v_add_f32_e32 v62, 1.0, v62
	v_add_f32_e32 v63, 1.0, v63
	v_rcp_f32_e32 v62, v62
	v_rcp_f32_e32 v63, v63
	v_add_f32_e32 v68, 1.0, v68
	v_add_f32_e32 v69, 1.0, v69
	v_add_f32_e32 v60, 1.0, v60
	v_pk_mul_f32 v[54:55], v[50:51], v[62:63]
	v_exp_f32_e32 v50, v52
	v_exp_f32_e32 v51, v53
	v_add_f32_e32 v61, 1.0, v61
	v_rcp_f32_e32 v68, v68
	v_add_f32_e32 v50, 1.0, v50
	v_add_f32_e32 v51, 1.0, v51
	v_rcp_f32_e32 v69, v69
	v_rcp_f32_e32 v60, v60
	v_rcp_f32_e32 v61, v61
	v_rcp_f32_e32 v50, v50
	v_rcp_f32_e32 v51, v51
	v_add_u32_e32 v66, 0x80, v135
	v_pk_mul_f32 v[56:57], v[56:57], v[52:53]
	v_mad_i64_i32 v[66:67], s[18:19], v66, s85, v[130:131]
	v_pk_mul_f32 v[58:59], v[58:59], v[68:69]
	v_pk_mul_f32 v[60:61], v[64:65], v[60:61]
	v_pk_mul_f32 v[56:57], v[56:57], v[50:51]
	v_lshl_add_u64 v[62:63], v[66:67], 0, v[114:115]
	v_cvt_pk_bf16_f32 v50, v58, v59
	v_cvt_pk_bf16_f32 v51, v60, v61
	v_cvt_pk_bf16_f32 v52, v54, v55
	v_cvt_pk_bf16_f32 v53, v56, v57
	global_store_dwordx4 v[62:63], v[50:53], off
	v_pk_mul_f32 v[48:49], v[48:49], v[44:45]
	v_exp_f32_e32 v44, v44
	v_exp_f32_e32 v52, v42
	v_exp_f32_e32 v53, v43
	v_pk_mul_f32 v[42:43], v[46:47], v[42:43]
	v_exp_f32_e32 v46, v34
	v_exp_f32_e32 v47, v35
	v_pk_mul_f32 v[34:35], v[38:39], v[34:35]
	v_exp_f32_e32 v45, v45
	v_add_f32_e32 v46, 1.0, v46
	v_add_f32_e32 v47, 1.0, v47
	v_rcp_f32_e32 v46, v46
	v_rcp_f32_e32 v47, v47
	v_add_f32_e32 v52, 1.0, v52
	v_add_f32_e32 v53, 1.0, v53
	v_add_f32_e32 v44, 1.0, v44
	v_pk_mul_f32 v[38:39], v[34:35], v[46:47]
	v_exp_f32_e32 v34, v36
	v_exp_f32_e32 v35, v37
	v_add_f32_e32 v45, 1.0, v45
	v_rcp_f32_e32 v52, v52
	v_add_f32_e32 v34, 1.0, v34
	v_add_f32_e32 v35, 1.0, v35
	v_rcp_f32_e32 v53, v53
	v_rcp_f32_e32 v44, v44
	v_rcp_f32_e32 v45, v45
	v_rcp_f32_e32 v34, v34
	v_rcp_f32_e32 v35, v35
	v_add_u32_e32 v50, 0x90, v135
	v_pk_mul_f32 v[40:41], v[40:41], v[36:37]
	v_mad_i64_i32 v[50:51], s[18:19], v50, s85, v[130:131]
	v_pk_mul_f32 v[42:43], v[42:43], v[52:53]
	v_pk_mul_f32 v[44:45], v[48:49], v[44:45]
	v_pk_mul_f32 v[40:41], v[40:41], v[34:35]
	v_lshl_add_u64 v[46:47], v[50:51], 0, v[114:115]
	v_cvt_pk_bf16_f32 v34, v42, v43
	v_cvt_pk_bf16_f32 v35, v44, v45
	v_cvt_pk_bf16_f32 v36, v38, v39
	v_cvt_pk_bf16_f32 v37, v40, v41
	global_store_dwordx4 v[46:47], v[34:37], off
	v_pk_mul_f32 v[32:33], v[32:33], v[28:29]
	v_exp_f32_e32 v28, v28
	v_exp_f32_e32 v36, v26
	v_exp_f32_e32 v37, v27
	v_pk_mul_f32 v[26:27], v[30:31], v[26:27]
	v_exp_f32_e32 v30, v18
	v_exp_f32_e32 v31, v19
	v_pk_mul_f32 v[18:19], v[22:23], v[18:19]
	v_exp_f32_e32 v29, v29
	v_add_f32_e32 v30, 1.0, v30
	v_add_f32_e32 v31, 1.0, v31
	v_rcp_f32_e32 v30, v30
	v_rcp_f32_e32 v31, v31
	v_add_f32_e32 v36, 1.0, v36
	v_add_f32_e32 v37, 1.0, v37
	v_add_f32_e32 v28, 1.0, v28
	v_pk_mul_f32 v[22:23], v[18:19], v[30:31]
	v_exp_f32_e32 v18, v20
	v_exp_f32_e32 v19, v21
	v_add_f32_e32 v29, 1.0, v29
	v_rcp_f32_e32 v36, v36
	v_add_f32_e32 v18, 1.0, v18
	v_add_f32_e32 v19, 1.0, v19
	v_rcp_f32_e32 v37, v37
	v_rcp_f32_e32 v28, v28
	v_rcp_f32_e32 v29, v29
	v_rcp_f32_e32 v18, v18
	v_rcp_f32_e32 v19, v19
	v_add_u32_e32 v34, 0xa0, v135
	v_pk_mul_f32 v[24:25], v[24:25], v[20:21]
	v_mad_i64_i32 v[34:35], s[18:19], v34, s85, v[130:131]
	v_pk_mul_f32 v[26:27], v[26:27], v[36:37]
	v_pk_mul_f32 v[28:29], v[32:33], v[28:29]
	v_pk_mul_f32 v[24:25], v[24:25], v[18:19]
	v_lshl_add_u64 v[30:31], v[34:35], 0, v[114:115]
	v_cvt_pk_bf16_f32 v18, v26, v27
	v_cvt_pk_bf16_f32 v19, v28, v29
	v_cvt_pk_bf16_f32 v20, v22, v23
	v_cvt_pk_bf16_f32 v21, v24, v25
	global_store_dwordx4 v[30:31], v[18:21], off
	v_pk_mul_f32 v[16:17], v[16:17], v[12:13]
	v_exp_f32_e32 v12, v12
	v_exp_f32_e32 v20, v10
	v_exp_f32_e32 v21, v11
	v_pk_mul_f32 v[10:11], v[14:15], v[10:11]
	v_exp_f32_e32 v14, v2
	v_exp_f32_e32 v15, v3
	v_pk_mul_f32 v[2:3], v[6:7], v[2:3]
	v_exp_f32_e32 v13, v13
	v_add_f32_e32 v14, 1.0, v14
	v_add_f32_e32 v15, 1.0, v15
	v_rcp_f32_e32 v14, v14
	v_rcp_f32_e32 v15, v15
	v_add_f32_e32 v20, 1.0, v20
	v_add_f32_e32 v21, 1.0, v21
	v_add_f32_e32 v12, 1.0, v12
	v_pk_mul_f32 v[6:7], v[2:3], v[14:15]
	v_exp_f32_e32 v2, v4
	v_exp_f32_e32 v3, v5
	v_add_f32_e32 v13, 1.0, v13
	v_rcp_f32_e32 v20, v20
	v_add_f32_e32 v2, 1.0, v2
	v_add_f32_e32 v3, 1.0, v3
	v_rcp_f32_e32 v21, v21
	v_rcp_f32_e32 v12, v12
	v_rcp_f32_e32 v13, v13
	v_rcp_f32_e32 v2, v2
	v_rcp_f32_e32 v3, v3
	v_add_u32_e32 v18, 0xb0, v135
	v_pk_mul_f32 v[8:9], v[8:9], v[4:5]
	v_mad_i64_i32 v[18:19], s[18:19], v18, s85, v[130:131]
	v_pk_mul_f32 v[10:11], v[10:11], v[20:21]
	v_pk_mul_f32 v[12:13], v[16:17], v[12:13]
	v_pk_mul_f32 v[8:9], v[8:9], v[2:3]
	v_lshl_add_u64 v[14:15], v[18:19], 0, v[114:115]
	v_cvt_pk_bf16_f32 v2, v10, v11
	v_cvt_pk_bf16_f32 v3, v12, v13
	v_cvt_pk_bf16_f32 v4, v6, v7
	v_cvt_pk_bf16_f32 v5, v8, v9
	s_mov_b64 s[18:19], -1
	global_store_dwordx4 v[14:15], v[2:5], off
	s_and_b64 vcc, exec, s[8:9]
	s_cbranch_vccz .Lzea_g1a
	s_barrier
.Lzea_g1a:
	s_andn2_b64 vcc, exec, s[6:7]
	s_cbranch_vccnz .LBB0_511
	s_andn2_b64 vcc, exec, s[4:5]
	s_cbranch_vccnz .LBB0_510
	s_barrier
	s_branch .LBB0_510

TB_L40000_exit:
.LBB0_1657:
	v_exp_f32_e32 v140, v122
	v_exp_f32_e32 v141, v123
	v_pk_mul_f32 v[122:123], v[126:127], v[122:123]
	v_exp_f32_e32 v126, v114
	v_exp_f32_e32 v127, v115
	v_pk_mul_f32 v[114:115], v[118:119], v[114:115]
	v_pk_mul_f32 v[128:129], v[128:129], v[124:125]
	v_add_f32_e32 v126, 1.0, v126
	v_add_f32_e32 v127, 1.0, v127
	v_rcp_f32_e32 v126, v126
	v_rcp_f32_e32 v127, v127
	v_exp_f32_e32 v124, v124
	v_exp_f32_e32 v125, v125
	s_lshl_b32 s6, s56, 8
	v_pk_mul_f32 v[118:119], v[114:115], v[126:127]
	v_exp_f32_e32 v114, v116
	v_exp_f32_e32 v115, v117
	v_mbcnt_lo_u32_b32 v130, -1, 0
	v_mbcnt_hi_u32_b32 v130, -1, v130
	s_add_i32 s6, s6, s36
	v_add_f32_e32 v140, 1.0, v140
	v_add_f32_e32 v141, 1.0, v141
	v_add_f32_e32 v124, 1.0, v124
	v_add_f32_e32 v125, 1.0, v125
	v_add_f32_e32 v114, 1.0, v114
	v_add_f32_e32 v115, 1.0, v115
	v_and_or_b32 v135, v130, 15, s6
	s_lshl_b32 s6, s51, 7
	v_lshrrev_b32_e32 v130, 1, v130
	v_rcp_f32_e32 v140, v140
	v_rcp_f32_e32 v141, v141
	v_rcp_f32_e32 v124, v124
	v_rcp_f32_e32 v125, v125
	v_rcp_f32_e32 v114, v114
	v_rcp_f32_e32 v115, v115
	v_and_or_b32 v130, v130, 24, s6
	v_readlane_b32 s6, v255, 26
	v_or_b32_e32 v136, s37, v130
	v_readlane_b32 s7, v255, 27
	v_ashrrev_i32_e32 v137, 31, v136
	v_pk_mul_f32 v[120:121], v[120:121], v[116:117]
	v_mov_b64_e32 v[130:131], s[6:7]
	v_mad_i64_i32 v[138:139], s[6:7], v135, s85, v[130:131]
	v_pk_mul_f32 v[122:123], v[122:123], v[140:141]
	v_pk_mul_f32 v[124:125], v[128:129], v[124:125]
	v_pk_mul_f32 v[120:121], v[120:121], v[114:115]
	v_lshlrev_b64 v[114:115], 1, v[136:137]
	v_lshl_add_u64 v[126:127], v[138:139], 0, v[114:115]
	v_cvt_pk_bf16_f32 v116, v122, v123
	v_cvt_pk_bf16_f32 v117, v124, v125
	v_cvt_pk_bf16_f32 v118, v118, v119
	v_cvt_pk_bf16_f32 v119, v120, v121
	global_store_dwordx4 v[126:127], v[116:119], off
	v_pk_mul_f32 v[112:113], v[112:113], v[108:109]
	v_exp_f32_e32 v108, v108
	v_exp_f32_e32 v118, v106
	v_exp_f32_e32 v119, v107
	v_pk_mul_f32 v[106:107], v[110:111], v[106:107]
	v_exp_f32_e32 v110, v98
	v_exp_f32_e32 v111, v99
	v_pk_mul_f32 v[98:99], v[102:103], v[98:99]
	v_exp_f32_e32 v109, v109
	v_add_f32_e32 v110, 1.0, v110
	v_add_f32_e32 v111, 1.0, v111
	v_rcp_f32_e32 v110, v110
	v_rcp_f32_e32 v111, v111
	v_add_f32_e32 v118, 1.0, v118
	v_add_f32_e32 v119, 1.0, v119
	v_add_f32_e32 v108, 1.0, v108
	v_pk_mul_f32 v[102:103], v[98:99], v[110:111]
	v_exp_f32_e32 v98, v100
	v_exp_f32_e32 v99, v101
	v_add_f32_e32 v109, 1.0, v109
	v_rcp_f32_e32 v118, v118
	v_add_f32_e32 v98, 1.0, v98
	v_add_f32_e32 v99, 1.0, v99
	v_rcp_f32_e32 v119, v119
	v_rcp_f32_e32 v108, v108
	v_rcp_f32_e32 v109, v109
	v_rcp_f32_e32 v98, v98
	v_rcp_f32_e32 v99, v99
	v_or_b32_e32 v116, 16, v135
	v_pk_mul_f32 v[104:105], v[104:105], v[100:101]
	v_mad_i64_i32 v[116:117], s[6:7], v116, s85, v[130:131]
	v_pk_mul_f32 v[106:107], v[106:107], v[118:119]
	v_pk_mul_f32 v[108:109], v[112:113], v[108:109]
	v_pk_mul_f32 v[104:105], v[104:105], v[98:99]
	v_lshl_add_u64 v[110:111], v[116:117], 0, v[114:115]
	v_cvt_pk_bf16_f32 v98, v106, v107
	v_cvt_pk_bf16_f32 v99, v108, v109
	v_cvt_pk_bf16_f32 v100, v102, v103
	v_cvt_pk_bf16_f32 v101, v104, v105
	global_store_dwordx4 v[110:111], v[98:101], off
	v_pk_mul_f32 v[96:97], v[96:97], v[92:93]
	v_exp_f32_e32 v92, v92
	v_exp_f32_e32 v100, v90
	v_exp_f32_e32 v101, v91
	v_pk_mul_f32 v[90:91], v[94:95], v[90:91]
	v_exp_f32_e32 v94, v82
	v_exp_f32_e32 v95, v83
	v_pk_mul_f32 v[82:83], v[86:87], v[82:83]
	v_exp_f32_e32 v93, v93
	v_add_f32_e32 v94, 1.0, v94
	v_add_f32_e32 v95, 1.0, v95
	v_rcp_f32_e32 v94, v94
	v_rcp_f32_e32 v95, v95
	v_add_f32_e32 v100, 1.0, v100
	v_add_f32_e32 v101, 1.0, v101
	v_add_f32_e32 v92, 1.0, v92
	v_pk_mul_f32 v[86:87], v[82:83], v[94:95]
	v_exp_f32_e32 v82, v84
	v_exp_f32_e32 v83, v85
	v_add_f32_e32 v93, 1.0, v93
	v_rcp_f32_e32 v100, v100
	v_add_f32_e32 v82, 1.0, v82
	v_add_f32_e32 v83, 1.0, v83
	v_rcp_f32_e32 v101, v101
	v_rcp_f32_e32 v92, v92
	v_rcp_f32_e32 v93, v93
	v_rcp_f32_e32 v82, v82
	v_rcp_f32_e32 v83, v83
	v_or_b32_e32 v98, 32, v135
	v_pk_mul_f32 v[88:89], v[88:89], v[84:85]
	v_mad_i64_i32 v[98:99], s[6:7], v98, s85, v[130:131]
	v_pk_mul_f32 v[90:91], v[90:91], v[100:101]
	v_pk_mul_f32 v[92:93], v[96:97], v[92:93]
	v_pk_mul_f32 v[88:89], v[88:89], v[82:83]
	v_lshl_add_u64 v[94:95], v[98:99], 0, v[114:115]
	v_cvt_pk_bf16_f32 v82, v90, v91
	v_cvt_pk_bf16_f32 v83, v92, v93
	v_cvt_pk_bf16_f32 v84, v86, v87
	v_cvt_pk_bf16_f32 v85, v88, v89
	global_store_dwordx4 v[94:95], v[82:85], off
	v_pk_mul_f32 v[80:81], v[80:81], v[76:77]
	v_exp_f32_e32 v76, v76
	v_exp_f32_e32 v84, v74
	v_exp_f32_e32 v85, v75
	v_pk_mul_f32 v[74:75], v[78:79], v[74:75]
	v_exp_f32_e32 v78, v66
	v_exp_f32_e32 v79, v67
	v_pk_mul_f32 v[66:67], v[70:71], v[66:67]
	v_exp_f32_e32 v77, v77
	v_add_f32_e32 v78, 1.0, v78
	v_add_f32_e32 v79, 1.0, v79
	v_rcp_f32_e32 v78, v78
	v_rcp_f32_e32 v79, v79
	v_add_f32_e32 v84, 1.0, v84
	v_add_f32_e32 v85, 1.0, v85
	v_add_f32_e32 v76, 1.0, v76
	v_pk_mul_f32 v[70:71], v[66:67], v[78:79]
	v_exp_f32_e32 v66, v68
	v_exp_f32_e32 v67, v69
	v_add_f32_e32 v77, 1.0, v77
	v_rcp_f32_e32 v84, v84
	v_add_f32_e32 v66, 1.0, v66
	v_add_f32_e32 v67, 1.0, v67
	v_rcp_f32_e32 v85, v85
	v_rcp_f32_e32 v76, v76
	v_rcp_f32_e32 v77, v77
	v_rcp_f32_e32 v66, v66
	v_rcp_f32_e32 v67, v67
	v_or_b32_e32 v82, 48, v135
	v_pk_mul_f32 v[72:73], v[72:73], v[68:69]
	v_mad_i64_i32 v[82:83], s[6:7], v82, s85, v[130:131]
	v_pk_mul_f32 v[74:75], v[74:75], v[84:85]
	v_pk_mul_f32 v[76:77], v[80:81], v[76:77]
	v_pk_mul_f32 v[72:73], v[72:73], v[66:67]
	v_lshl_add_u64 v[78:79], v[82:83], 0, v[114:115]
	v_cvt_pk_bf16_f32 v66, v74, v75
	v_cvt_pk_bf16_f32 v67, v76, v77
	v_cvt_pk_bf16_f32 v68, v70, v71
	v_cvt_pk_bf16_f32 v69, v72, v73
	global_store_dwordx4 v[78:79], v[66:69], off
	v_pk_mul_f32 v[64:65], v[64:65], v[60:61]
	v_exp_f32_e32 v60, v60
	v_exp_f32_e32 v68, v58
	v_exp_f32_e32 v69, v59
	v_pk_mul_f32 v[58:59], v[62:63], v[58:59]
	v_exp_f32_e32 v62, v50
	v_exp_f32_e32 v63, v51
	v_pk_mul_f32 v[50:51], v[54:55], v[50:51]
	v_exp_f32_e32 v61, v61
	v_add_f32_e32 v62, 1.0, v62
	v_add_f32_e32 v63, 1.0, v63
	v_rcp_f32_e32 v62, v62
	v_rcp_f32_e32 v63, v63
	v_add_f32_e32 v68, 1.0, v68
	v_add_f32_e32 v69, 1.0, v69
	v_add_f32_e32 v60, 1.0, v60
	v_pk_mul_f32 v[54:55], v[50:51], v[62:63]
	v_exp_f32_e32 v50, v52
	v_exp_f32_e32 v51, v53
	v_add_f32_e32 v61, 1.0, v61
	v_rcp_f32_e32 v68, v68
	v_add_f32_e32 v50, 1.0, v50
	v_add_f32_e32 v51, 1.0, v51
	v_rcp_f32_e32 v69, v69
	v_rcp_f32_e32 v60, v60
	v_rcp_f32_e32 v61, v61
	v_rcp_f32_e32 v50, v50
	v_rcp_f32_e32 v51, v51
	v_add_u32_e32 v66, 0x80, v135
	v_pk_mul_f32 v[56:57], v[56:57], v[52:53]
	v_mad_i64_i32 v[66:67], s[6:7], v66, s85, v[130:131]
	v_pk_mul_f32 v[58:59], v[58:59], v[68:69]
	v_pk_mul_f32 v[60:61], v[64:65], v[60:61]
	v_pk_mul_f32 v[56:57], v[56:57], v[50:51]
	v_lshl_add_u64 v[62:63], v[66:67], 0, v[114:115]
	v_cvt_pk_bf16_f32 v50, v58, v59
	v_cvt_pk_bf16_f32 v51, v60, v61
	v_cvt_pk_bf16_f32 v52, v54, v55
	v_cvt_pk_bf16_f32 v53, v56, v57
	global_store_dwordx4 v[62:63], v[50:53], off
	v_pk_mul_f32 v[48:49], v[48:49], v[44:45]
	v_exp_f32_e32 v44, v44
	v_exp_f32_e32 v52, v42
	v_exp_f32_e32 v53, v43
	v_pk_mul_f32 v[42:43], v[46:47], v[42:43]
	v_exp_f32_e32 v46, v34
	v_exp_f32_e32 v47, v35
	v_pk_mul_f32 v[34:35], v[38:39], v[34:35]
	v_exp_f32_e32 v45, v45
	v_add_f32_e32 v46, 1.0, v46
	v_add_f32_e32 v47, 1.0, v47
	v_rcp_f32_e32 v46, v46
	v_rcp_f32_e32 v47, v47
	v_add_f32_e32 v52, 1.0, v52
	v_add_f32_e32 v53, 1.0, v53
	v_add_f32_e32 v44, 1.0, v44
	v_pk_mul_f32 v[38:39], v[34:35], v[46:47]
	v_exp_f32_e32 v34, v36
	v_exp_f32_e32 v35, v37
	v_add_f32_e32 v45, 1.0, v45
	v_rcp_f32_e32 v52, v52
	v_add_f32_e32 v34, 1.0, v34
	v_add_f32_e32 v35, 1.0, v35
	v_rcp_f32_e32 v53, v53
	v_rcp_f32_e32 v44, v44
	v_rcp_f32_e32 v45, v45
	v_rcp_f32_e32 v34, v34
	v_rcp_f32_e32 v35, v35
	v_add_u32_e32 v50, 0x90, v135
	v_pk_mul_f32 v[40:41], v[40:41], v[36:37]
	v_mad_i64_i32 v[50:51], s[6:7], v50, s85, v[130:131]
	v_pk_mul_f32 v[42:43], v[42:43], v[52:53]
	v_pk_mul_f32 v[44:45], v[48:49], v[44:45]
	v_pk_mul_f32 v[40:41], v[40:41], v[34:35]
	v_lshl_add_u64 v[46:47], v[50:51], 0, v[114:115]
	v_cvt_pk_bf16_f32 v34, v42, v43
	v_cvt_pk_bf16_f32 v35, v44, v45
	v_cvt_pk_bf16_f32 v36, v38, v39
	v_cvt_pk_bf16_f32 v37, v40, v41
	global_store_dwordx4 v[46:47], v[34:37], off
	v_pk_mul_f32 v[32:33], v[32:33], v[28:29]
	v_exp_f32_e32 v28, v28
	v_exp_f32_e32 v36, v26
	v_exp_f32_e32 v37, v27
	v_pk_mul_f32 v[26:27], v[30:31], v[26:27]
	v_exp_f32_e32 v30, v18
	v_exp_f32_e32 v31, v19
	v_pk_mul_f32 v[18:19], v[22:23], v[18:19]
	v_exp_f32_e32 v29, v29
	v_add_f32_e32 v30, 1.0, v30
	v_add_f32_e32 v31, 1.0, v31
	v_rcp_f32_e32 v30, v30
	v_rcp_f32_e32 v31, v31
	v_add_f32_e32 v36, 1.0, v36
	v_add_f32_e32 v37, 1.0, v37
	v_add_f32_e32 v28, 1.0, v28
	v_pk_mul_f32 v[22:23], v[18:19], v[30:31]
	v_exp_f32_e32 v18, v20
	v_exp_f32_e32 v19, v21
	v_add_f32_e32 v29, 1.0, v29
	v_rcp_f32_e32 v36, v36
	v_add_f32_e32 v18, 1.0, v18
	v_add_f32_e32 v19, 1.0, v19
	v_rcp_f32_e32 v37, v37
	v_rcp_f32_e32 v28, v28
	v_rcp_f32_e32 v29, v29
	v_rcp_f32_e32 v18, v18
	v_rcp_f32_e32 v19, v19
	v_add_u32_e32 v34, 0xa0, v135
	v_pk_mul_f32 v[24:25], v[24:25], v[20:21]
	v_mad_i64_i32 v[34:35], s[6:7], v34, s85, v[130:131]
	v_pk_mul_f32 v[26:27], v[26:27], v[36:37]
	v_pk_mul_f32 v[28:29], v[32:33], v[28:29]
	v_pk_mul_f32 v[24:25], v[24:25], v[18:19]
	v_lshl_add_u64 v[30:31], v[34:35], 0, v[114:115]
	v_cvt_pk_bf16_f32 v18, v26, v27
	v_cvt_pk_bf16_f32 v19, v28, v29
	v_cvt_pk_bf16_f32 v20, v22, v23
	v_cvt_pk_bf16_f32 v21, v24, v25
	global_store_dwordx4 v[30:31], v[18:21], off
	v_pk_mul_f32 v[16:17], v[16:17], v[12:13]
	v_exp_f32_e32 v12, v12
	v_exp_f32_e32 v20, v10
	v_exp_f32_e32 v21, v11
	v_pk_mul_f32 v[10:11], v[14:15], v[10:11]
	v_exp_f32_e32 v14, v2
	v_exp_f32_e32 v15, v3
	v_pk_mul_f32 v[2:3], v[6:7], v[2:3]
	v_exp_f32_e32 v13, v13
	v_add_f32_e32 v14, 1.0, v14
	v_add_f32_e32 v15, 1.0, v15
	v_rcp_f32_e32 v14, v14
	v_rcp_f32_e32 v15, v15
	v_add_f32_e32 v20, 1.0, v20
	v_add_f32_e32 v21, 1.0, v21
	v_add_f32_e32 v12, 1.0, v12
	v_pk_mul_f32 v[6:7], v[2:3], v[14:15]
	v_exp_f32_e32 v2, v4
	v_exp_f32_e32 v3, v5
	v_add_f32_e32 v13, 1.0, v13
	v_rcp_f32_e32 v20, v20
	v_add_f32_e32 v2, 1.0, v2
	v_add_f32_e32 v3, 1.0, v3
	v_rcp_f32_e32 v21, v21
	v_rcp_f32_e32 v12, v12
	v_rcp_f32_e32 v13, v13
	v_rcp_f32_e32 v2, v2
	v_rcp_f32_e32 v3, v3
	v_add_u32_e32 v18, 0xb0, v135
	v_pk_mul_f32 v[8:9], v[8:9], v[4:5]
	v_mad_i64_i32 v[18:19], s[6:7], v18, s85, v[130:131]
	v_pk_mul_f32 v[10:11], v[10:11], v[20:21]
	v_pk_mul_f32 v[12:13], v[16:17], v[12:13]
	v_pk_mul_f32 v[8:9], v[8:9], v[2:3]
	v_lshl_add_u64 v[14:15], v[18:19], 0, v[114:115]
	v_cvt_pk_bf16_f32 v2, v10, v11
	v_cvt_pk_bf16_f32 v3, v12, v13
	v_cvt_pk_bf16_f32 v4, v6, v7
	v_cvt_pk_bf16_f32 v5, v8, v9
	s_mov_b64 s[6:7], -1
	global_store_dwordx4 v[14:15], v[2:5], off
	s_and_b64 vcc, exec, s[10:11]
	s_cbranch_vccz .Lzea_g1b
	s_barrier
.Lzea_g1b:
	s_andn2_b64 vcc, exec, s[4:5]
	s_cbranch_vccnz .LBB0_1650
	s_andn2_b64 vcc, exec, s[8:9]
	s_cbranch_vccnz .LBB0_1649
	s_barrier
	s_branch .LBB0_1649
